# attention phase: static s_setprio 1 for waves 4-7 (set once at phase entry, reset at exit) to de-synchronise the two waves per SIMD, on top of v034
# speedup vs baseline: 1.0008x; 1.0008x over previous
; __device__ __forceinline__ void attn_phase(const Params& p, int layer, LAS unsigned char* lds, int tid) {
;     OPQ_TID(tid);
;     const bf16* PROJ = (const bf16*)(p.ws + WS_PROJ);
;     bf16* YC = (bf16*)(p.ws + WS_Y + (size_t)M * 1024);
;     LAS bf16* Ks = (LAS bf16*)lds;
;     LAS bf16* Vt = (LAS bf16*)(lds + 27648);
;     const int wave = tid >> 6, lane = tid & 63, l15 = lane & 15, quad = lane >> 4;
;     const int g4 = wave >> 1, qh = wave & 1;
;     constexpr int NQT = (L + 63) / 64;
;     constexpr float LOG2E = 1.4426950408889634f;
;     for (int item = blockIdx.x; item < BATCH * 2 * NQT; item += gridDim.x) {
;         const int qt = item % NQT, bk = item / NQT, kvh = bk & 1, b = bk >> 1;
;         const int t0 = qt * 64; const size_t mb = (size_t)b * L;
;         __syncthreads();
; #pragma unroll
;         for (int i = 0; i < 3; ++i) { const int idx = tid + i * 512, row = idx >> 3, ch = idx & 7;
;             int s = t0 - 128 + row; s = s < 0 ? 0 : (s > L - 1 ? L - 1 : s);
;             const bf16* src = PROJ + (mb + s) * PC + 1792 + kvh * 64 + ch * 8;
;             const u32x4 kv = *(const u32x4*)src; *(LAS u32x4*)(Ks + row * 72 + ch * 8) = kv;
;             const u32x4 vv = *(const u32x4*)(src + 128);
;             LAS bf16* vd = Vt + (ch * 8) * 200 + row;
;             vd[0] = (bf16)(vv.x & 0xffffu); vd[200] = (bf16)(vv.x >> 16); vd[400] = (bf16)(vv.y & 0xffffu); vd[600] = (bf16)(vv.y >> 16);
;             vd[800] = (bf16)(vv.z & 0xffffu); vd[1000] = (bf16)(vv.z >> 16); vd[1200] = (bf16)(vv.w & 0xffffu); vd[1400] = (bf16)(vv.w >> 16); }
;         __syncthreads();
;         const int hq = kvh * 4 + g4;
;         const float slope2 = exp2f(-(float)(hq + 1)) * LOG2E, sink2 = INP(24)[layer * 8 + hq] * LOG2E;
; #pragma unroll 1
;         for (int ct = 0; ct < 2; ++ct) {
;             const int kt0 = qh * 2 + ct;
;             int tq = t0 + kt0 * 16 + l15; const int t = tq; tq = tq > L - 1 ? L - 1 : tq;
;             bf16x8 qf[2];
; #pragma unroll
;             for (int ks = 0; ks < 2; ++ks) qf[ks] = *(const bf16x8*)(PROJ + (mb + tq) * PC + 1280 + hq * 64 + ks * 32 + quad * 8);
;             const LAS bf16* Kb = Ks + (kt0 * 16 + l15) * 72 + quad * 8;
;             const LAS bf16* Vb = Vt + l15 * 200 + kt0 * 16 + quad * 4;
;             const float fd = (float)(l15 + 128 - quad * 4);
;             f32x4 oacc[4]; float inv;
.LBB0_499:
	s_and_b64 vcc, exec, s[8:9]
	s_cbranch_vccz .LBB0_589
	s_cmp_eq_u32 s6, 2
	s_mov_b64 s[70:71], -1
	s_cbranch_scc0 .LBB0_589
	v_readlane_b32 s0, v248, 20
	v_readlane_b32 s1, v248, 21
	v_mov_b32_e32 v0, v188
	s_andn2_b64 vcc, exec, s[0:1]
	s_cbranch_vccnz .LBB0_512
	v_cmp_gt_u32_e32 vcc, 0x100, v188
	s_cbranch_vccnz .Lattn_prio
	s_setprio 1
.Lattn_prio:
	s_waitcnt vmcnt(0)
	v_and_b32_e32 v40, 15, v0
	v_bfe_u32 v3, v0, 4, 2
	v_mul_u32_u24_e32 v9, 0x190, v40
	s_waitcnt vmcnt(0)
	v_lshlrev_b32_e32 v44, 2, v3
	v_lshlrev_b32_e32 v8, 3, v3
	v_or_b32_e32 v3, 0x80, v40
	v_add3_u32 v45, 0, v9, v8
	v_sub_u32_e32 v9, v3, v44
	v_add_u32_e32 v10, -1, v9
	v_cvt_f32_u32_e32 v47, v10
	v_add_u32_e32 v10, -2, v9
	v_cvt_f32_u32_e32 v48, v10
	v_add_u32_e32 v10, -3, v9
	v_cvt_f32_u32_e32 v50, v10
	v_add_u32_e32 v10, -16, v9
	v_cvt_f32_u32_e32 v52, v10
	v_subrev_u32_e32 v10, 17, v9
	v_cvt_f32_u32_e32 v53, v10
	v_subrev_u32_e32 v10, 18, v9
	v_cvt_f32_u32_e32 v54, v10
	v_subrev_u32_e32 v10, 19, v9
	v_cvt_f32_u32_e32 v55, v10
	v_subrev_u32_e32 v10, 32, v9
	v_cvt_f32_u32_e32 v56, v10
	v_subrev_u32_e32 v10, 33, v9
	v_cvt_f32_u32_e32 v57, v10
	v_subrev_u32_e32 v10, 34, v9
	v_cvt_f32_u32_e32 v58, v10
	v_subrev_u32_e32 v10, 35, v9
	v_cvt_f32_u32_e32 v59, v10
	v_subrev_u32_e32 v10, 48, v9
	v_cvt_f32_u32_e32 v60, v10
	v_subrev_u32_e32 v10, 49, v9
	v_cvt_f32_u32_e32 v61, v10
	v_subrev_u32_e32 v10, 50, v9
	v_cvt_f32_u32_e32 v62, v10
	v_subrev_u32_e32 v10, 51, v9
	v_cvt_f32_u32_e32 v63, v10
	v_subrev_u32_e32 v10, 64, v9
	v_cvt_f32_u32_e32 v64, v10
	v_add_u32_e32 v10, 0xffffffbf, v9
	v_cvt_f32_u32_e32 v65, v10
	v_add_u32_e32 v10, 0xffffffbe, v9
	v_cvt_f32_u32_e32 v66, v10
	v_add_u32_e32 v10, 0xffffffbd, v9
	v_cvt_f32_u32_e32 v67, v10
	v_add_u32_e32 v10, 0xffffffb0, v9
	v_cvt_f32_u32_e32 v68, v10
	v_add_u32_e32 v10, 0xffffffaf, v9
	v_cvt_f32_u32_e32 v69, v10
	v_add_u32_e32 v10, 0xffffffae, v9
	v_cvt_f32_u32_e32 v70, v10
	v_add_u32_e32 v10, 0xffffffad, v9
	v_cvt_f32_u32_e32 v71, v10
	v_add_u32_e32 v10, 0xffffffa0, v9
	v_cvt_f32_u32_e32 v72, v10
	v_add_u32_e32 v10, 0xffffff9f, v9
	v_cvt_f32_u32_e32 v73, v10
	v_add_u32_e32 v10, 0xffffff9e, v9
	v_readlane_b32 s0, v247, 53
	v_lshlrev_b32_e32 v4, 3, v0
	v_cvt_f32_u32_e32 v74, v10
	v_add_u32_e32 v10, 0xffffff9d, v9
	v_readlane_b32 s1, v247, 54
	v_and_b32_e32 v4, 56, v4
	v_cvt_f32_u32_e32 v75, v10
	v_add_u32_e32 v10, 0xffffff90, v9
	v_lshl_add_u32 v5, v4, 1, 0
	s_movk_i32 s1, 0x18e
	v_cvt_f32_u32_e32 v76, v10
	v_add_u32_e32 v10, 0xffffff8f, v9
	v_mad_u32_u24 v7, v4, s1, v5
	v_cvt_f32_u32_e32 v77, v10
	v_add_u32_e32 v10, 0xffffff8e, v9
	s_movk_i32 s1, 0x7f
	v_cvt_f32_u32_e32 v78, v10
	v_add_u32_e32 v10, 0xffffff8d, v9
	v_cmp_lt_u32_e64 s[46:47], s1, v9
	s_movk_i32 s1, 0x80
	v_cvt_f32_u32_e32 v79, v10
	v_add_u32_e32 v10, 0xffffff80, v9
	v_cmp_lt_u32_e64 s[48:49], s1, v9
	s_movk_i32 s1, 0x81
	v_cvt_f32_i32_e32 v80, v10
	v_add_u32_e32 v10, 0xffffff7f, v9
	v_cmp_lt_u32_e64 s[50:51], s1, v9
	s_movk_i32 s1, 0x82
	v_lshrrev_b32_e32 v6, 5, v0
	v_cvt_f32_ubyte0_e32 v46, v9
	v_cvt_f32_i32_e32 v81, v10
	v_add_u32_e32 v10, 0xffffff7e, v9
	v_cmp_lt_u32_e64 s[52:53], s1, v9
	v_add_u32_e32 v9, 0xffffff7d, v9
	v_or_b32_e32 v116, 0x81, v44
	v_or_b32_e32 v117, 0x82, v44
	v_or_b32_e32 v118, 0x83, v44
	v_ashrrev_i32_e32 v41, 7, v0
	v_and_b32_e32 v1, 63, v0
	v_and_b32_e32 v42, 2, v6
	v_and_b32_e32 v6, 48, v0
	v_cvt_f32_i32_e32 v82, v10
	v_cvt_f32_i32_e32 v83, v9
	v_cmp_gt_u32_e64 s[54:55], v116, v3
	v_cmp_gt_u32_e64 s[56:57], v117, v3
	v_cmp_gt_u32_e64 s[58:59], v118, v3
	v_ashrrev_i32_e32 v119, 3, v0
	v_add_u32_e32 v3, 0x200, v0
	v_add_u32_e32 v0, 0x400, v0
	v_lshlrev_b32_e32 v1, 2, v1
	v_readlane_b32 s4, v248, 22
	s_movk_i32 s1, 0x90
	v_ashrrev_i32_e32 v121, 3, v3
	v_ashrrev_i32_e32 v123, 3, v0
	v_or_b32_e32 v49, 2, v44
	v_or_b32_e32 v51, 3, v44
	v_xor_b32_e32 v84, 64, v1
	v_xor_b32_e32 v85, 0x80, v1
	v_mov_b32_e32 v9, v2
	v_readlane_b32 s5, v248, 23
	v_mul_lo_u32 v1, v119, s1
	v_lshl_add_u32 v120, v119, 1, v7
	v_mul_lo_u32 v3, v121, s1
	v_lshl_add_u32 v122, v121, 1, v7
	v_mul_lo_u32 v0, v123, s1
	v_lshl_add_u32 v124, v123, 1, v7
	v_mov_b32_e32 v7, v2
	s_lshl_b32 s0, s0, 3
	v_add_u32_e32 v43, 0, v6
	v_cmp_gt_u32_e64 s[38:39], v44, v40
	v_cmp_lt_u32_e64 s[40:41], v44, v40
	v_cmp_gt_u32_e64 s[42:43], v49, v40
	v_cmp_gt_u32_e64 s[44:45], v51, v40
	v_or_b32_e32 v86, 1, v44
	v_or_b32_e32 v87, 16, v44
	v_or_b32_e32 v88, 17, v44
	v_or_b32_e32 v89, 18, v44
	v_or_b32_e32 v90, 19, v44
	v_or_b32_e32 v91, 32, v44
	v_or_b32_e32 v92, 33, v44
	v_or_b32_e32 v93, 34, v44
	v_or_b32_e32 v94, 35, v44
	v_or_b32_e32 v95, 48, v44
	v_or_b32_e32 v96, 49, v44
	v_or_b32_e32 v97, 50, v44
	v_or_b32_e32 v98, 51, v44
	v_or_b32_e32 v99, 64, v44
	v_or_b32_e32 v100, 0x41, v44
	v_or_b32_e32 v101, 0x42, v44
	v_or_b32_e32 v102, 0x43, v44
	v_or_b32_e32 v103, 0x50, v44
	v_or_b32_e32 v104, 0x51, v44
	v_or_b32_e32 v105, 0x52, v44
	v_or_b32_e32 v106, 0x53, v44
	v_or_b32_e32 v107, 0x60, v44
	v_or_b32_e32 v108, 0x61, v44
	v_or_b32_e32 v109, 0x62, v44
	v_or_b32_e32 v110, 0x63, v44
	v_or_b32_e32 v111, 0x70, v44
	v_or_b32_e32 v112, 0x71, v44
	v_or_b32_e32 v113, 0x72, v44
	v_or_b32_e32 v114, 0x73, v44
	v_or_b32_e32 v115, 0x80, v44
	v_lshl_add_u64 v[28:29], s[4:5], 0, v[8:9]
	v_lshl_add_u64 v[30:31], s[66:67], 0, v[6:7]
	v_lshlrev_b32_e32 v32, 1, v4
	v_add_u32_e32 v125, v5, v1
	v_add_u32_e32 v126, v5, v3
	v_add_u32_e32 v127, v5, v0
	s_mov_b32 s1, s64
	s_branch .LBB0_504

; #define INP(i) (p.in[opq(i)])
; #define OPQ_TID(tid) asm volatile("" : "+v"(tid))
; #define WAVE_IDS(tid) const int lane = tid & 63, wave = __builtin_amdgcn_readfirstlane(tid >> 6), gw = blockIdx.x * 8 + wave, ngw = gridDim.x * 8; (void)lane; (void)wave; (void)gw; (void)ngw
; __device__ __forceinline__ void prep1_phase(const Params& p, int layer, int tid) {
;     OPQ_TID(tid); WAVE_IDS(tid);
;     const bf16* PROJ = (const bf16*)(p.ws + WS_PROJ);
;     bf16* XA = (bf16*)(p.ws + WS_Y); bf16* XVv = XA + (size_t)M * 256; bf16* SR = (bf16*)(p.ws + WS_SR); bf16* SK = (bf16*)(p.ws + WS_SK);
;     const float* mu = INP(8) + (size_t)layer * 1024;
;     f32x4 mu4[4];
; #pragma unroll
;     for (int s = 0; s < 4; ++s) mu4[s] = *(const f32x4*)(mu + s * 256 + 4 * lane);
;     const int c4 = 4 * lane;
;     for (int m0 = gw; m0 < M; m0 += 4 * ngw) {
;         u32x2 ra[4][4], rb[4][4];
; #pragma unroll
;         for (int q = 0; q < 4; ++q) { const int m = m0 + q * ngw;
;             if (m < M) { const int t = m % L; const bf16* cur = PROJ + (size_t)m * PC;
; #pragma unroll
;                 for (int s = 0; s < 4; ++s) { ra[q][s] = *(const u32x2*)(cur + s * 256 + c4); rb[q][s] = (u32x2){0u, 0u}; if (t > 0) rb[q][s] = *(const u32x2*)(cur - PC + s * 256 + c4); } } }
.LBB0_512:
	s_setprio 0
	v_mov_b32_e32 v0, v188
	v_readlane_b32 s1, v248, 7
	v_readfirstlane_b32 s0, v0
	s_ashr_i32 s0, s0, 6
	s_add_i32 s8, s0, s1
	v_readlane_b32 s12, v247, 46
	s_mov_b32 s10, 8
	s_cmp_gt_i32 s8, 0x100ff
	v_readlane_b32 s13, v247, 47
	s_cbranch_scc1 .LBB0_588
	v_readlane_b32 s0, v247, 53
	v_readlane_b32 s1, v247, 54
	s_ashr_i32 s11, s10, 31
	s_lshl_b64 s[0:1], s[0:1], 12
	s_lshl_b64 s[10:11], s[10:11], 3
	s_add_u32 s10, s12, s10
	s_addc_u32 s11, s13, s11
	s_load_dwordx2 s[10:11], s[10:11], 0x0
	v_and_b32_e32 v1, 63, v0
	v_lshlrev_b32_e32 v0, 4, v1
	s_waitcnt vmcnt(0)
	v_lshlrev_b32_e32 v20, 3, v1
	v_mov_b32_e32 v21, v2
	s_waitcnt lgkmcnt(0)
	s_add_u32 s0, s10, s0
	s_addc_u32 s1, s11, s1
	global_load_dwordx4 v[4:7], v0, s[0:1]
	global_load_dwordx4 v[8:11], v0, s[0:1] offset:1024
	global_load_dwordx4 v[12:15], v0, s[0:1] offset:2048
	global_load_dwordx4 v[16:19], v0, s[0:1] offset:3072
	v_readlane_b32 s0, v248, 10
	v_readlane_b32 s1, v248, 11
	s_ashr_i32 s9, s8, 31
	s_lshl_b64 s[10:11], s[8:9], 9
	v_lshl_add_u64 v[22:23], s[0:1], 0, v[20:21]
	v_readlane_b32 s0, v248, 8
	v_readlane_b32 s1, v248, 9
	s_mul_i32 s2, s8, 0x1800
	v_lshlrev_b32_e32 v0, 2, v1
	v_lshl_add_u64 v[24:25], s[0:1], 0, v[20:21]
	v_readlane_b32 s0, v248, 5
	v_readlane_b32 s1, v248, 6
	v_cmp_lt_u32_e64 s[38:39], 15, v1
	v_cmp_lt_u32_e64 s[40:41], 31, v1
	v_lshl_add_u64 v[26:27], s[0:1], 0, v[20:21]
	s_lshl_b32 s0, s95, 4
	s_add_u32 s12, s82, s10
	s_addc_u32 s13, s83, s11
	s_ashr_i32 s93, s92, 31
	s_lshl_b64 s[14:15], s[92:93], 9
	s_mul_hi_i32 s1, s8, 0x1800
	s_add_u32 s16, s82, s2
	v_lshl_add_u64 v[28:29], s[60:61], 0, v[20:21]
	s_addc_u32 s17, s83, s1
	s_branch .LBB0_516
